# v15 + P3 passC carry-in loop software-pipelined with a second register set (loads of p+1 in flight during FMAs of p)
# baseline (speedup 1.0000x reference)
; DI void hgrn_passC(LAS unsigned char* lds, const bf16* QG, const float* OL, const float* DS, const float* DSC, const bf16* ZG, const float* gnorm, bf16* OG, float* state_out, int bid, int G, int tid) {
;     ...
;         for (int p = 0; p < nprev; ++p) {
; #pragma unroll
;             for (int j = 0; j < 8; ++j) {
;                 const f32x4 d = *(const f32x4*)(DSC + (h * 16 + p) * 128 + 16 * j + 4 * g);
; #pragma unroll
;                 for (int i = 0; i < 4; ++i) S[j][i] = S[j][i] * d[i] + DS[((size_t)(h * 16 + p) * 128 + 16 * j + 4 * g + i) * 128 + 16 * wave + lr];
;             }
.Lmy_c3_entry:
	s_mov_b32 s100, 0
	s_add_i32 s42, s35, s37
	s_ashr_i32 s43, s42, 31
	s_lshl_b64 s[42:43], s[42:43], 16
	s_ashr_i32 s9, s8, 31
	v_mov_b32_e32 v59, s43
	v_or_b32_e32 v58, s42, v30
	v_lshl_add_u64 v[64:65], s[8:9], 2, v[20:21]
	v_lshl_add_u64 v[60:61], v[22:23], 0, v[58:59]
	v_or_b32_e32 v62, 0x2000, v58
	v_mov_b32_e32 v63, s43
	v_or_b32_e32 v78, 0x2200, v58
	v_mov_b32_e32 v79, s43
	v_or_b32_e32 v80, 0x2400, v58
	v_mov_b32_e32 v81, s43
	v_or_b32_e32 v82, 0x2600, v58
	v_mov_b32_e32 v83, s43
	global_load_dwordx4 v[0:3], v[64:65], off
	global_load_dwordx4 v[4:7], v[64:65], off offset:64
	v_lshl_add_u64 v[62:63], v[22:23], 0, v[62:63]
	v_lshl_add_u64 v[78:79], v[22:23], 0, v[78:79]
	v_lshl_add_u64 v[80:81], v[22:23], 0, v[80:81]
	v_lshl_add_u64 v[82:83], v[22:23], 0, v[82:83]
	global_load_dword v98, v[60:61], off
	global_load_dword v99, v[60:61], off offset:512
	global_load_dword v100, v[60:61], off offset:1024
	global_load_dword v101, v[60:61], off offset:1536
	global_load_dword v102, v[62:63], off
	global_load_dword v103, v[78:79], off
	global_load_dword v104, v[80:81], off
	global_load_dword v105, v[82:83], off
	v_or_b32_e32 v60, 0x4000, v58
	v_mov_b32_e32 v61, s43
	v_lshl_add_u64 v[82:83], v[22:23], 0, v[60:61]
	v_or_b32_e32 v60, 0x4200, v58
	v_lshl_add_u64 v[84:85], v[22:23], 0, v[60:61]
	v_or_b32_e32 v60, 0x4400, v58
	v_lshl_add_u64 v[86:87], v[22:23], 0, v[60:61]
	v_or_b32_e32 v60, 0x4600, v58
	v_or_b32_e32 v90, 0x6000, v58
	v_mov_b32_e32 v91, s43
	v_or_b32_e32 v92, 0x6200, v58
	v_mov_b32_e32 v93, s43
	v_or_b32_e32 v94, 0x6400, v58
	v_mov_b32_e32 v95, s43
	v_or_b32_e32 v96, 0x6600, v58
	v_mov_b32_e32 v97, s43
	v_lshl_add_u64 v[88:89], v[22:23], 0, v[60:61]
	global_load_dwordx4 v[60:63], v[64:65], off offset:128
	global_load_dwordx4 v[78:81], v[64:65], off offset:192
	v_lshl_add_u64 v[90:91], v[22:23], 0, v[90:91]
	v_lshl_add_u64 v[92:93], v[22:23], 0, v[92:93]
	v_lshl_add_u64 v[94:95], v[22:23], 0, v[94:95]
	v_lshl_add_u64 v[96:97], v[22:23], 0, v[96:97]
	global_load_dword v106, v[82:83], off
	global_load_dword v107, v[84:85], off
	global_load_dword v108, v[86:87], off
	global_load_dword v109, v[88:89], off
	global_load_dword v110, v[90:91], off
	global_load_dword v111, v[92:93], off
	global_load_dword v112, v[94:95], off
	global_load_dword v113, v[96:97], off
	v_or_b32_e32 v82, 0x8000, v58
	v_mov_b32_e32 v83, s43
	v_lshl_add_u64 v[90:91], v[22:23], 0, v[82:83]
	v_or_b32_e32 v82, 0x8200, v58
	v_lshl_add_u64 v[92:93], v[22:23], 0, v[82:83]
	v_or_b32_e32 v82, 0x8400, v58
	v_or_b32_e32 v114, 0xa000, v58
	v_mov_b32_e32 v115, s43
	v_lshl_add_u64 v[94:95], v[22:23], 0, v[82:83]
	v_or_b32_e32 v82, 0x8600, v58
	v_lshl_add_u64 v[114:115], v[22:23], 0, v[114:115]
	v_or_b32_e32 v116, 0xa200, v58
	v_mov_b32_e32 v117, s43
	v_or_b32_e32 v118, 0xa400, v58
	v_mov_b32_e32 v119, s43
	v_or_b32_e32 v120, 0xa600, v58
	v_mov_b32_e32 v121, s43
	v_lshl_add_u64 v[96:97], v[22:23], 0, v[82:83]
	global_load_dwordx4 v[82:85], v[64:65], off offset:256
	global_load_dwordx4 v[86:89], v[64:65], off offset:320
	v_lshl_add_u64 v[116:117], v[22:23], 0, v[116:117]
	v_lshl_add_u64 v[118:119], v[22:23], 0, v[118:119]
	v_lshl_add_u64 v[120:121], v[22:23], 0, v[120:121]
	global_load_dword v122, v[90:91], off
	global_load_dword v123, v[92:93], off
	global_load_dword v124, v[94:95], off
	global_load_dword v125, v[96:97], off
	global_load_dword v126, v[114:115], off
	global_load_dword v127, v[116:117], off
	s_nop 0
	global_load_dword v114, v[118:119], off
	global_load_dword v115, v[120:121], off
	v_or_b32_e32 v90, 0xc000, v58
	v_mov_b32_e32 v91, s43
	v_lshl_add_u64 v[116:117], v[22:23], 0, v[90:91]
	v_or_b32_e32 v90, 0xc200, v58
	v_lshl_add_u64 v[118:119], v[22:23], 0, v[90:91]
	v_or_b32_e32 v90, 0xc400, v58
	v_lshl_add_u64 v[120:121], v[22:23], 0, v[90:91]
	v_or_b32_e32 v90, 0xc600, v58
	v_lshl_add_u64 v[128:129], v[22:23], 0, v[90:91]
	global_load_dwordx4 v[90:93], v[64:65], off offset:384
	global_load_dwordx4 v[94:97], v[64:65], off offset:448
	v_or_b32_e32 v64, 0xe000, v58
	v_mov_b32_e32 v65, s43
	v_lshl_add_u64 v[64:65], v[22:23], 0, v[64:65]
	v_or_b32_e32 v130, 0xe200, v58
	v_mov_b32_e32 v131, s43
	v_or_b32_e32 v132, 0xe400, v58
	v_mov_b32_e32 v133, s43
	v_or_b32_e32 v58, 0xe600, v58
	v_lshl_add_u64 v[130:131], v[22:23], 0, v[130:131]
	v_lshl_add_u64 v[132:133], v[22:23], 0, v[132:133]
	v_lshl_add_u64 v[58:59], v[22:23], 0, v[58:59]
	global_load_dword v116, v[116:117], off
	s_nop 0
	global_load_dword v117, v[118:119], off
	s_nop 0
	global_load_dword v118, v[120:121], off
	global_load_dword v119, v[128:129], off
	s_nop 0
	global_load_dword v64, v[64:65], off
	s_nop 0
	global_load_dword v65, v[130:131], off
	global_load_dword v120, v[132:133], off
	global_load_dword v121, v[58:59], off
	s_add_i32 s37, s37, 1
	s_addk_i32 s8, 0x80
; DI void hgrn_passC(LAS unsigned char* lds, const bf16* QG, const float* OL, const float* DS, const float* DSC, const bf16* ZG, const float* gnorm, bf16* OG, float* state_out, int bid, int G, int tid) {
;     ...
;         for (int p = 0; p < nprev; ++p) {
; #pragma unroll
;             for (int j = 0; j < 8; ++j) {
;                 const f32x4 d = *(const f32x4*)(DSC + (h * 16 + p) * 128 + 16 * j + 4 * g);
; #pragma unroll
;                 for (int i = 0; i < 4; ++i) S[j][i] = S[j][i] * d[i] + DS[((size_t)(h * 16 + p) * 128 + 16 * j + 4 * g + i) * 128 + 16 * wave + lr];
;             }
.Lmy_c3_A:
	s_cmp_lt_u32 s37, s34
	s_cbranch_scc0 .Lmy_c3_A_drain
	s_add_i32 s42, s35, s37
	s_ashr_i32 s43, s42, 31
	s_lshl_b64 s[42:43], s[42:43], 16
	s_ashr_i32 s9, s8, 31
	v_mov_b32_e32 v157, s43
	v_or_b32_e32 v156, s42, v30
	v_lshl_add_u64 v[162:163], s[8:9], 2, v[20:21]
	v_lshl_add_u64 v[158:159], v[22:23], 0, v[156:157]
	v_or_b32_e32 v160, 0x2000, v156
	v_mov_b32_e32 v161, s43
	v_or_b32_e32 v164, 0x2200, v156
	v_mov_b32_e32 v165, s43
	v_or_b32_e32 v166, 0x2400, v156
	v_mov_b32_e32 v167, s43
	v_or_b32_e32 v168, 0x2600, v156
	v_mov_b32_e32 v169, s43
	global_load_dwordx4 v[148:151], v[162:163], off
	global_load_dwordx4 v[152:155], v[162:163], off offset:64
	v_lshl_add_u64 v[160:161], v[22:23], 0, v[160:161]
	v_lshl_add_u64 v[164:165], v[22:23], 0, v[164:165]
	v_lshl_add_u64 v[166:167], v[22:23], 0, v[166:167]
	v_lshl_add_u64 v[168:169], v[22:23], 0, v[168:169]
	global_load_dword v184, v[158:159], off
	global_load_dword v185, v[158:159], off offset:512
	global_load_dword v186, v[158:159], off offset:1024
	global_load_dword v187, v[158:159], off offset:1536
	global_load_dword v188, v[160:161], off
	global_load_dword v189, v[164:165], off
	global_load_dword v190, v[166:167], off
	global_load_dword v191, v[168:169], off
	v_or_b32_e32 v158, 0x4000, v156
	v_mov_b32_e32 v159, s43
	v_lshl_add_u64 v[168:169], v[22:23], 0, v[158:159]
	v_or_b32_e32 v158, 0x4200, v156
	v_lshl_add_u64 v[170:171], v[22:23], 0, v[158:159]
	v_or_b32_e32 v158, 0x4400, v156
	v_lshl_add_u64 v[172:173], v[22:23], 0, v[158:159]
	v_or_b32_e32 v158, 0x4600, v156
	v_or_b32_e32 v176, 0x6000, v156
	v_mov_b32_e32 v177, s43
	v_or_b32_e32 v178, 0x6200, v156
	v_mov_b32_e32 v179, s43
	v_or_b32_e32 v180, 0x6400, v156
	v_mov_b32_e32 v181, s43
	v_or_b32_e32 v182, 0x6600, v156
	v_mov_b32_e32 v183, s43
	v_lshl_add_u64 v[174:175], v[22:23], 0, v[158:159]
	global_load_dwordx4 v[158:161], v[162:163], off offset:128
	global_load_dwordx4 v[164:167], v[162:163], off offset:192
	v_lshl_add_u64 v[176:177], v[22:23], 0, v[176:177]
	v_lshl_add_u64 v[178:179], v[22:23], 0, v[178:179]
	v_lshl_add_u64 v[180:181], v[22:23], 0, v[180:181]
	v_lshl_add_u64 v[182:183], v[22:23], 0, v[182:183]
	global_load_dword v192, v[168:169], off
	global_load_dword v193, v[170:171], off
	global_load_dword v194, v[172:173], off
	global_load_dword v195, v[174:175], off
	global_load_dword v196, v[176:177], off
	global_load_dword v197, v[178:179], off
	global_load_dword v198, v[180:181], off
	global_load_dword v199, v[182:183], off
	v_or_b32_e32 v168, 0x8000, v156
	v_mov_b32_e32 v169, s43
	v_lshl_add_u64 v[176:177], v[22:23], 0, v[168:169]
	v_or_b32_e32 v168, 0x8200, v156
	v_lshl_add_u64 v[178:179], v[22:23], 0, v[168:169]
	v_or_b32_e32 v168, 0x8400, v156
	v_or_b32_e32 v200, 0xa000, v156
	v_mov_b32_e32 v201, s43
	v_lshl_add_u64 v[180:181], v[22:23], 0, v[168:169]
	v_or_b32_e32 v168, 0x8600, v156
	v_lshl_add_u64 v[200:201], v[22:23], 0, v[200:201]
	v_or_b32_e32 v202, 0xa200, v156
	v_mov_b32_e32 v203, s43
	v_or_b32_e32 v204, 0xa400, v156
	v_mov_b32_e32 v205, s43
	v_or_b32_e32 v206, 0xa600, v156
	v_mov_b32_e32 v207, s43
	v_lshl_add_u64 v[182:183], v[22:23], 0, v[168:169]
	global_load_dwordx4 v[168:171], v[162:163], off offset:256
	global_load_dwordx4 v[172:175], v[162:163], off offset:320
	v_lshl_add_u64 v[202:203], v[22:23], 0, v[202:203]
	v_lshl_add_u64 v[204:205], v[22:23], 0, v[204:205]
	v_lshl_add_u64 v[206:207], v[22:23], 0, v[206:207]
	global_load_dword v208, v[176:177], off
	global_load_dword v209, v[178:179], off
	global_load_dword v210, v[180:181], off
	global_load_dword v211, v[182:183], off
	global_load_dword v212, v[200:201], off
	global_load_dword v213, v[202:203], off
	s_nop 0
	global_load_dword v200, v[204:205], off
	global_load_dword v201, v[206:207], off
	v_or_b32_e32 v176, 0xc000, v156
	v_mov_b32_e32 v177, s43
	v_lshl_add_u64 v[202:203], v[22:23], 0, v[176:177]
	v_or_b32_e32 v176, 0xc200, v156
	v_lshl_add_u64 v[204:205], v[22:23], 0, v[176:177]
	v_or_b32_e32 v176, 0xc400, v156
	v_lshl_add_u64 v[206:207], v[22:23], 0, v[176:177]
	v_or_b32_e32 v176, 0xc600, v156
	v_lshl_add_u64 v[214:215], v[22:23], 0, v[176:177]
	global_load_dwordx4 v[176:179], v[162:163], off offset:384
	global_load_dwordx4 v[180:183], v[162:163], off offset:448
	v_or_b32_e32 v162, 0xe000, v156
	v_mov_b32_e32 v163, s43
	v_lshl_add_u64 v[162:163], v[22:23], 0, v[162:163]
	v_or_b32_e32 v216, 0xe200, v156
	v_mov_b32_e32 v217, s43
	v_or_b32_e32 v218, 0xe400, v156
	v_mov_b32_e32 v219, s43
	v_or_b32_e32 v156, 0xe600, v156
	v_lshl_add_u64 v[216:217], v[22:23], 0, v[216:217]
	v_lshl_add_u64 v[218:219], v[22:23], 0, v[218:219]
	v_lshl_add_u64 v[156:157], v[22:23], 0, v[156:157]
	global_load_dword v202, v[202:203], off
	s_nop 0
	global_load_dword v203, v[204:205], off
	s_nop 0
	global_load_dword v204, v[206:207], off
	global_load_dword v205, v[214:215], off
	s_nop 0
	global_load_dword v162, v[162:163], off
	s_nop 0
	global_load_dword v163, v[216:217], off
	global_load_dword v206, v[218:219], off
	global_load_dword v207, v[156:157], off
	s_add_i32 s37, s37, 1
	s_addk_i32 s8, 0x80
	s_cmp_eq_u32 s100, 14
	s_cselect_b64 s[42:43], -1, 0
	s_and_b64 s[42:43], s[6:7], s[42:43]
	s_and_b64 vcc, exec, s[42:43]
	s_waitcnt vmcnt(63)
	v_pk_fma_f32 v[54:55], v[54:55], v[0:1], v[98:99]
	s_waitcnt vmcnt(63)
	v_pk_fma_f32 v[56:57], v[56:57], v[2:3], v[100:101]
	s_waitcnt vmcnt(63)
	v_pk_fma_f32 v[52:53], v[52:53], v[4:5], v[102:103]
	s_waitcnt vmcnt(63)
	v_pk_fma_f32 v[50:51], v[50:51], v[6:7], v[104:105]
	s_waitcnt vmcnt(63)
	v_pk_fma_f32 v[48:49], v[48:49], v[60:61], v[106:107]
	s_waitcnt vmcnt(63)
	v_pk_fma_f32 v[46:47], v[46:47], v[62:63], v[108:109]
	s_waitcnt vmcnt(62)
	v_pk_fma_f32 v[44:45], v[44:45], v[78:79], v[110:111]
	s_waitcnt vmcnt(60)
	v_pk_fma_f32 v[42:43], v[42:43], v[80:81], v[112:113]
	s_waitcnt vmcnt(56)
	v_pk_fma_f32 v[40:41], v[40:41], v[82:83], v[122:123]
	s_waitcnt vmcnt(54)
	v_pk_fma_f32 v[38:39], v[38:39], v[84:85], v[124:125]
	s_waitcnt vmcnt(52)
	v_pk_fma_f32 v[36:37], v[36:37], v[86:87], v[126:127]
	s_waitcnt vmcnt(50)
	v_pk_fma_f32 v[34:35], v[34:35], v[88:89], v[114:115]
	s_waitcnt vmcnt(46)
	v_pk_fma_f32 v[14:15], v[14:15], v[90:91], v[116:117]
	s_waitcnt vmcnt(44)
	v_pk_fma_f32 v[12:13], v[12:13], v[92:93], v[118:119]
	s_waitcnt vmcnt(42)
	v_pk_fma_f32 v[10:11], v[10:11], v[94:95], v[64:65]
	s_waitcnt vmcnt(40)
	v_pk_fma_f32 v[8:9], v[8:9], v[96:97], v[120:121]
	s_cbranch_vccz .Lmy_c3_A_nosp
; #define LAS __attribute__((address_space(3)))
; DI unsigned pk2(float lo, float hi) { const f32x2 v = {lo, hi}; return __builtin_bit_cast(unsigned, __builtin_convertvector(v, bf16x2_t)); }
; DI void hgrn_passC(LAS unsigned char* lds, const bf16* QG, const float* OL, const float* DS, const float* DSC, const bf16* ZG, const float* gnorm, bf16* OG, float* state_out, int bid, int G, int tid) {
;     ...
;         for (int p = 0; p < nprev; ++p) {
; #pragma unroll
;             for (int j = 0; j < 8; ++j) {
;                 const f32x4 d = *(const f32x4*)(DSC + (h * 16 + p) * 128 + 16 * j + 4 * g);
; #pragma unroll
;                 for (int i = 0; i < 4; ++i) S[j][i] = S[j][i] * d[i] + DS[((size_t)(h * 16 + p) * 128 + 16 * j + 4 * g + i) * 128 + 16 * wave + lr];
;             }
;             if (p == 14 && sc == 15) {
; #pragma unroll
;                 for (int j = 0; j < 8; ++j) { v2u w; w.x = pk2(S[j][0], S[j][1]); w.y = pk2(S[j][2], S[j][3]); *(LAS v2u*)(lds + HC_SINT + (16 * wave + lr) * 272 + 2 * (16 * j + 4 * g)) = w; }
	v_cvt_pk_bf16_f32 v0, v54, v55
	v_cvt_pk_bf16_f32 v1, v56, v57
	v_add_u32_e32 v4, v69, v70
	v_cvt_pk_bf16_f32 v2, v52, v53
	v_cvt_pk_bf16_f32 v3, v50, v51
	ds_write2_b64 v4, v[0:1], v[2:3] offset1:4
	v_cvt_pk_bf16_f32 v0, v48, v49
	v_cvt_pk_bf16_f32 v1, v46, v47
	v_cvt_pk_bf16_f32 v2, v44, v45
	v_cvt_pk_bf16_f32 v3, v42, v43
	ds_write2_b64 v4, v[0:1], v[2:3] offset0:8 offset1:12
	v_cvt_pk_bf16_f32 v0, v40, v41
	v_cvt_pk_bf16_f32 v1, v38, v39
	v_cvt_pk_bf16_f32 v2, v36, v37
	v_cvt_pk_bf16_f32 v3, v34, v35
	ds_write2_b64 v4, v[0:1], v[2:3] offset0:16 offset1:20
	v_cvt_pk_bf16_f32 v0, v14, v15
	v_cvt_pk_bf16_f32 v1, v12, v13
	v_cvt_pk_bf16_f32 v2, v10, v11
	v_cvt_pk_bf16_f32 v3, v8, v9
	ds_write2_b64 v4, v[0:1], v[2:3] offset0:24 offset1:28
.Lmy_c3_A_nosp:
	s_add_i32 s100, s100, 1
	s_cmp_lt_u32 s37, s34
	s_cbranch_scc0 .Lmy_c3_B_drain
	s_add_i32 s42, s35, s37
	s_ashr_i32 s43, s42, 31
	s_lshl_b64 s[42:43], s[42:43], 16
	s_ashr_i32 s9, s8, 31
	v_mov_b32_e32 v59, s43
	v_or_b32_e32 v58, s42, v30
	v_lshl_add_u64 v[64:65], s[8:9], 2, v[20:21]
	v_lshl_add_u64 v[60:61], v[22:23], 0, v[58:59]
	v_or_b32_e32 v62, 0x2000, v58
	v_mov_b32_e32 v63, s43
	v_or_b32_e32 v78, 0x2200, v58
	v_mov_b32_e32 v79, s43
	v_or_b32_e32 v80, 0x2400, v58
	v_mov_b32_e32 v81, s43
	v_or_b32_e32 v82, 0x2600, v58
	v_mov_b32_e32 v83, s43
	global_load_dwordx4 v[0:3], v[64:65], off
	global_load_dwordx4 v[4:7], v[64:65], off offset:64
	v_lshl_add_u64 v[62:63], v[22:23], 0, v[62:63]
	v_lshl_add_u64 v[78:79], v[22:23], 0, v[78:79]
	v_lshl_add_u64 v[80:81], v[22:23], 0, v[80:81]
	v_lshl_add_u64 v[82:83], v[22:23], 0, v[82:83]
	global_load_dword v98, v[60:61], off
	global_load_dword v99, v[60:61], off offset:512
	global_load_dword v100, v[60:61], off offset:1024
	global_load_dword v101, v[60:61], off offset:1536
	global_load_dword v102, v[62:63], off
	global_load_dword v103, v[78:79], off
	global_load_dword v104, v[80:81], off
	global_load_dword v105, v[82:83], off
	v_or_b32_e32 v60, 0x4000, v58
	v_mov_b32_e32 v61, s43
	v_lshl_add_u64 v[82:83], v[22:23], 0, v[60:61]
	v_or_b32_e32 v60, 0x4200, v58
	v_lshl_add_u64 v[84:85], v[22:23], 0, v[60:61]
	v_or_b32_e32 v60, 0x4400, v58
	v_lshl_add_u64 v[86:87], v[22:23], 0, v[60:61]
	v_or_b32_e32 v60, 0x4600, v58
	v_or_b32_e32 v90, 0x6000, v58
	v_mov_b32_e32 v91, s43
	v_or_b32_e32 v92, 0x6200, v58
	v_mov_b32_e32 v93, s43
	v_or_b32_e32 v94, 0x6400, v58
	v_mov_b32_e32 v95, s43
	v_or_b32_e32 v96, 0x6600, v58
	v_mov_b32_e32 v97, s43
	v_lshl_add_u64 v[88:89], v[22:23], 0, v[60:61]
	global_load_dwordx4 v[60:63], v[64:65], off offset:128
	global_load_dwordx4 v[78:81], v[64:65], off offset:192
	v_lshl_add_u64 v[90:91], v[22:23], 0, v[90:91]
	v_lshl_add_u64 v[92:93], v[22:23], 0, v[92:93]
	v_lshl_add_u64 v[94:95], v[22:23], 0, v[94:95]
	v_lshl_add_u64 v[96:97], v[22:23], 0, v[96:97]
	global_load_dword v106, v[82:83], off
	global_load_dword v107, v[84:85], off
	global_load_dword v108, v[86:87], off
	global_load_dword v109, v[88:89], off
	global_load_dword v110, v[90:91], off
	global_load_dword v111, v[92:93], off
	global_load_dword v112, v[94:95], off
	global_load_dword v113, v[96:97], off
	v_or_b32_e32 v82, 0x8000, v58
	v_mov_b32_e32 v83, s43
	v_lshl_add_u64 v[90:91], v[22:23], 0, v[82:83]
	v_or_b32_e32 v82, 0x8200, v58
	v_lshl_add_u64 v[92:93], v[22:23], 0, v[82:83]
	v_or_b32_e32 v82, 0x8400, v58
	v_or_b32_e32 v114, 0xa000, v58
	v_mov_b32_e32 v115, s43
	v_lshl_add_u64 v[94:95], v[22:23], 0, v[82:83]
	v_or_b32_e32 v82, 0x8600, v58
	v_lshl_add_u64 v[114:115], v[22:23], 0, v[114:115]
	v_or_b32_e32 v116, 0xa200, v58
	v_mov_b32_e32 v117, s43
	v_or_b32_e32 v118, 0xa400, v58
	v_mov_b32_e32 v119, s43
	v_or_b32_e32 v120, 0xa600, v58
	v_mov_b32_e32 v121, s43
	v_lshl_add_u64 v[96:97], v[22:23], 0, v[82:83]
	global_load_dwordx4 v[82:85], v[64:65], off offset:256
	global_load_dwordx4 v[86:89], v[64:65], off offset:320
	v_lshl_add_u64 v[116:117], v[22:23], 0, v[116:117]
	v_lshl_add_u64 v[118:119], v[22:23], 0, v[118:119]
	v_lshl_add_u64 v[120:121], v[22:23], 0, v[120:121]
	global_load_dword v122, v[90:91], off
	global_load_dword v123, v[92:93], off
	global_load_dword v124, v[94:95], off
	global_load_dword v125, v[96:97], off
	global_load_dword v126, v[114:115], off
	global_load_dword v127, v[116:117], off
	s_nop 0
	global_load_dword v114, v[118:119], off
	global_load_dword v115, v[120:121], off
	v_or_b32_e32 v90, 0xc000, v58
	v_mov_b32_e32 v91, s43
	v_lshl_add_u64 v[116:117], v[22:23], 0, v[90:91]
	v_or_b32_e32 v90, 0xc200, v58
	v_lshl_add_u64 v[118:119], v[22:23], 0, v[90:91]
	v_or_b32_e32 v90, 0xc400, v58
	v_lshl_add_u64 v[120:121], v[22:23], 0, v[90:91]
	v_or_b32_e32 v90, 0xc600, v58
	v_lshl_add_u64 v[128:129], v[22:23], 0, v[90:91]
	global_load_dwordx4 v[90:93], v[64:65], off offset:384
	global_load_dwordx4 v[94:97], v[64:65], off offset:448
	v_or_b32_e32 v64, 0xe000, v58
	v_mov_b32_e32 v65, s43
	v_lshl_add_u64 v[64:65], v[22:23], 0, v[64:65]
	v_or_b32_e32 v130, 0xe200, v58
	v_mov_b32_e32 v131, s43
	v_or_b32_e32 v132, 0xe400, v58
	v_mov_b32_e32 v133, s43
	v_or_b32_e32 v58, 0xe600, v58
	v_lshl_add_u64 v[130:131], v[22:23], 0, v[130:131]
	v_lshl_add_u64 v[132:133], v[22:23], 0, v[132:133]
	v_lshl_add_u64 v[58:59], v[22:23], 0, v[58:59]
	global_load_dword v116, v[116:117], off
	s_nop 0
	global_load_dword v117, v[118:119], off
	s_nop 0
	global_load_dword v118, v[120:121], off
	global_load_dword v119, v[128:129], off
	s_nop 0
	global_load_dword v64, v[64:65], off
	s_nop 0
	global_load_dword v65, v[130:131], off
	global_load_dword v120, v[132:133], off
	global_load_dword v121, v[58:59], off
	s_add_i32 s37, s37, 1
	s_addk_i32 s8, 0x80
	s_cmp_eq_u32 s100, 14
	s_cselect_b64 s[42:43], -1, 0
	s_and_b64 s[42:43], s[6:7], s[42:43]
	s_and_b64 vcc, exec, s[42:43]
	s_waitcnt vmcnt(63)
	v_pk_fma_f32 v[54:55], v[54:55], v[148:149], v[184:185]
	s_waitcnt vmcnt(63)
	v_pk_fma_f32 v[56:57], v[56:57], v[150:151], v[186:187]
	s_waitcnt vmcnt(63)
	v_pk_fma_f32 v[52:53], v[52:53], v[152:153], v[188:189]
	s_waitcnt vmcnt(63)
	v_pk_fma_f32 v[50:51], v[50:51], v[154:155], v[190:191]
	s_waitcnt vmcnt(63)
	v_pk_fma_f32 v[48:49], v[48:49], v[158:159], v[192:193]
	s_waitcnt vmcnt(63)
	v_pk_fma_f32 v[46:47], v[46:47], v[160:161], v[194:195]
	s_waitcnt vmcnt(62)
	v_pk_fma_f32 v[44:45], v[44:45], v[164:165], v[196:197]
	s_waitcnt vmcnt(60)
	v_pk_fma_f32 v[42:43], v[42:43], v[166:167], v[198:199]
	s_waitcnt vmcnt(56)
	v_pk_fma_f32 v[40:41], v[40:41], v[168:169], v[208:209]
	s_waitcnt vmcnt(54)
	v_pk_fma_f32 v[38:39], v[38:39], v[170:171], v[210:211]
	s_waitcnt vmcnt(52)
	v_pk_fma_f32 v[36:37], v[36:37], v[172:173], v[212:213]
	s_waitcnt vmcnt(50)
	v_pk_fma_f32 v[34:35], v[34:35], v[174:175], v[200:201]
	s_waitcnt vmcnt(46)
	v_pk_fma_f32 v[14:15], v[14:15], v[176:177], v[202:203]
	s_waitcnt vmcnt(44)
	v_pk_fma_f32 v[12:13], v[12:13], v[178:179], v[204:205]
	s_waitcnt vmcnt(42)
	v_pk_fma_f32 v[10:11], v[10:11], v[180:181], v[162:163]
	s_waitcnt vmcnt(40)
	v_pk_fma_f32 v[8:9], v[8:9], v[182:183], v[206:207]
	s_cbranch_vccz .Lmy_c3_B_nosp
; #define LAS __attribute__((address_space(3)))
; DI unsigned pk2(float lo, float hi) { const f32x2 v = {lo, hi}; return __builtin_bit_cast(unsigned, __builtin_convertvector(v, bf16x2_t)); }
; DI void hgrn_passC(LAS unsigned char* lds, const bf16* QG, const float* OL, const float* DS, const float* DSC, const bf16* ZG, const float* gnorm, bf16* OG, float* state_out, int bid, int G, int tid) {
;     ...
;         for (int p = 0; p < nprev; ++p) {
; #pragma unroll
;             for (int j = 0; j < 8; ++j) {
;                 const f32x4 d = *(const f32x4*)(DSC + (h * 16 + p) * 128 + 16 * j + 4 * g);
; #pragma unroll
;                 for (int i = 0; i < 4; ++i) S[j][i] = S[j][i] * d[i] + DS[((size_t)(h * 16 + p) * 128 + 16 * j + 4 * g + i) * 128 + 16 * wave + lr];
;             }
;             if (p == 14 && sc == 15) {
; #pragma unroll
;                 for (int j = 0; j < 8; ++j) { v2u w; w.x = pk2(S[j][0], S[j][1]); w.y = pk2(S[j][2], S[j][3]); *(LAS v2u*)(lds + HC_SINT + (16 * wave + lr) * 272 + 2 * (16 * j + 4 * g)) = w; }
;             }
;         }
	v_cvt_pk_bf16_f32 v148, v54, v55
	v_cvt_pk_bf16_f32 v149, v56, v57
	v_add_u32_e32 v152, v69, v70
	v_cvt_pk_bf16_f32 v150, v52, v53
	v_cvt_pk_bf16_f32 v151, v50, v51
	ds_write2_b64 v152, v[148:149], v[150:151] offset1:4
	v_cvt_pk_bf16_f32 v148, v48, v49
	v_cvt_pk_bf16_f32 v149, v46, v47
	v_cvt_pk_bf16_f32 v150, v44, v45
	v_cvt_pk_bf16_f32 v151, v42, v43
	ds_write2_b64 v152, v[148:149], v[150:151] offset0:8 offset1:12
	v_cvt_pk_bf16_f32 v148, v40, v41
	v_cvt_pk_bf16_f32 v149, v38, v39
	v_cvt_pk_bf16_f32 v150, v36, v37
	v_cvt_pk_bf16_f32 v151, v34, v35
	ds_write2_b64 v152, v[148:149], v[150:151] offset0:16 offset1:20
	v_cvt_pk_bf16_f32 v148, v14, v15
	v_cvt_pk_bf16_f32 v149, v12, v13
	v_cvt_pk_bf16_f32 v150, v10, v11
	v_cvt_pk_bf16_f32 v151, v8, v9
	ds_write2_b64 v152, v[148:149], v[150:151] offset0:24 offset1:28
.Lmy_c3_B_nosp:
	s_add_i32 s100, s100, 1
	s_branch .Lmy_c3_A
.Lmy_c3_A_drain:
	s_cmp_eq_u32 s100, 14
	s_cselect_b64 s[42:43], -1, 0
	s_and_b64 s[42:43], s[6:7], s[42:43]
	s_and_b64 vcc, exec, s[42:43]
	s_waitcnt vmcnt(36)
	v_pk_fma_f32 v[54:55], v[54:55], v[0:1], v[98:99]
	s_waitcnt vmcnt(34)
	v_pk_fma_f32 v[56:57], v[56:57], v[2:3], v[100:101]
	s_waitcnt vmcnt(32)
	v_pk_fma_f32 v[52:53], v[52:53], v[4:5], v[102:103]
	s_waitcnt vmcnt(30)
	v_pk_fma_f32 v[50:51], v[50:51], v[6:7], v[104:105]
	s_waitcnt vmcnt(26)
	v_pk_fma_f32 v[48:49], v[48:49], v[60:61], v[106:107]
	s_waitcnt vmcnt(24)
	v_pk_fma_f32 v[46:47], v[46:47], v[62:63], v[108:109]
	s_waitcnt vmcnt(22)
	v_pk_fma_f32 v[44:45], v[44:45], v[78:79], v[110:111]
	s_waitcnt vmcnt(20)
	v_pk_fma_f32 v[42:43], v[42:43], v[80:81], v[112:113]
	s_waitcnt vmcnt(16)
	v_pk_fma_f32 v[40:41], v[40:41], v[82:83], v[122:123]
	s_waitcnt vmcnt(14)
	v_pk_fma_f32 v[38:39], v[38:39], v[84:85], v[124:125]
	s_waitcnt vmcnt(12)
	v_pk_fma_f32 v[36:37], v[36:37], v[86:87], v[126:127]
	s_waitcnt vmcnt(10)
	v_pk_fma_f32 v[34:35], v[34:35], v[88:89], v[114:115]
	s_waitcnt vmcnt(6)
	v_pk_fma_f32 v[14:15], v[14:15], v[90:91], v[116:117]
	s_waitcnt vmcnt(4)
	v_pk_fma_f32 v[12:13], v[12:13], v[92:93], v[118:119]
	s_waitcnt vmcnt(2)
	v_pk_fma_f32 v[10:11], v[10:11], v[94:95], v[64:65]
	s_waitcnt vmcnt(0)
	v_pk_fma_f32 v[8:9], v[8:9], v[96:97], v[120:121]
	s_cbranch_vccz .LBB0_455
	v_cvt_pk_bf16_f32 v0, v54, v55
	v_cvt_pk_bf16_f32 v1, v56, v57
	v_add_u32_e32 v4, v69, v70
	v_cvt_pk_bf16_f32 v2, v52, v53
	v_cvt_pk_bf16_f32 v3, v50, v51
	ds_write2_b64 v4, v[0:1], v[2:3] offset1:4
	v_cvt_pk_bf16_f32 v0, v48, v49
	v_cvt_pk_bf16_f32 v1, v46, v47
	v_cvt_pk_bf16_f32 v2, v44, v45
	v_cvt_pk_bf16_f32 v3, v42, v43
	ds_write2_b64 v4, v[0:1], v[2:3] offset0:8 offset1:12
	v_cvt_pk_bf16_f32 v0, v40, v41
	v_cvt_pk_bf16_f32 v1, v38, v39
	v_cvt_pk_bf16_f32 v2, v36, v37
	v_cvt_pk_bf16_f32 v3, v34, v35
	ds_write2_b64 v4, v[0:1], v[2:3] offset0:16 offset1:20
	v_cvt_pk_bf16_f32 v0, v14, v15
	v_cvt_pk_bf16_f32 v1, v12, v13
	v_cvt_pk_bf16_f32 v2, v10, v11
	v_cvt_pk_bf16_f32 v3, v8, v9
	ds_write2_b64 v4, v[0:1], v[2:3] offset0:24 offset1:28
	s_branch .LBB0_455
.Lmy_c3_B_drain:
	s_cmp_eq_u32 s100, 14
	s_cselect_b64 s[42:43], -1, 0
	s_and_b64 s[42:43], s[6:7], s[42:43]
	s_and_b64 vcc, exec, s[42:43]
	s_waitcnt vmcnt(36)
	v_pk_fma_f32 v[54:55], v[54:55], v[148:149], v[184:185]
	s_waitcnt vmcnt(34)
	v_pk_fma_f32 v[56:57], v[56:57], v[150:151], v[186:187]
	s_waitcnt vmcnt(32)
	v_pk_fma_f32 v[52:53], v[52:53], v[152:153], v[188:189]
	s_waitcnt vmcnt(30)
	v_pk_fma_f32 v[50:51], v[50:51], v[154:155], v[190:191]
	s_waitcnt vmcnt(26)
	v_pk_fma_f32 v[48:49], v[48:49], v[158:159], v[192:193]
	s_waitcnt vmcnt(24)
	v_pk_fma_f32 v[46:47], v[46:47], v[160:161], v[194:195]
	s_waitcnt vmcnt(22)
	v_pk_fma_f32 v[44:45], v[44:45], v[164:165], v[196:197]
	s_waitcnt vmcnt(20)
	v_pk_fma_f32 v[42:43], v[42:43], v[166:167], v[198:199]
	s_waitcnt vmcnt(16)
	v_pk_fma_f32 v[40:41], v[40:41], v[168:169], v[208:209]
	s_waitcnt vmcnt(14)
	v_pk_fma_f32 v[38:39], v[38:39], v[170:171], v[210:211]
	s_waitcnt vmcnt(12)
	v_pk_fma_f32 v[36:37], v[36:37], v[172:173], v[212:213]
	s_waitcnt vmcnt(10)
	v_pk_fma_f32 v[34:35], v[34:35], v[174:175], v[200:201]
	s_waitcnt vmcnt(6)
	v_pk_fma_f32 v[14:15], v[14:15], v[176:177], v[202:203]
	s_waitcnt vmcnt(4)
	v_pk_fma_f32 v[12:13], v[12:13], v[178:179], v[204:205]
	s_waitcnt vmcnt(2)
	v_pk_fma_f32 v[10:11], v[10:11], v[180:181], v[162:163]
	s_waitcnt vmcnt(0)
	v_pk_fma_f32 v[8:9], v[8:9], v[182:183], v[206:207]
	s_cbranch_vccz .LBB0_455
	v_cvt_pk_bf16_f32 v148, v54, v55
	v_cvt_pk_bf16_f32 v149, v56, v57
	v_add_u32_e32 v152, v69, v70
	v_cvt_pk_bf16_f32 v150, v52, v53
	v_cvt_pk_bf16_f32 v151, v50, v51
	ds_write2_b64 v152, v[148:149], v[150:151] offset1:4
	v_cvt_pk_bf16_f32 v148, v48, v49
	v_cvt_pk_bf16_f32 v149, v46, v47
	v_cvt_pk_bf16_f32 v150, v44, v45
	v_cvt_pk_bf16_f32 v151, v42, v43
	ds_write2_b64 v152, v[148:149], v[150:151] offset0:8 offset1:12
	v_cvt_pk_bf16_f32 v148, v40, v41
	v_cvt_pk_bf16_f32 v149, v38, v39
	v_cvt_pk_bf16_f32 v150, v36, v37
	v_cvt_pk_bf16_f32 v151, v34, v35
	ds_write2_b64 v152, v[148:149], v[150:151] offset0:16 offset1:20
	v_cvt_pk_bf16_f32 v148, v14, v15
	v_cvt_pk_bf16_f32 v149, v12, v13
	v_cvt_pk_bf16_f32 v150, v10, v11
	v_cvt_pk_bf16_f32 v151, v8, v9
	ds_write2_b64 v152, v[148:149], v[150:151] offset0:24 offset1:28
